# seams 2..5 without L2 write-back/invalidate (run-time XCC_ID check): P2 B items and P2b tokens remapped so every producer->consumer pair from P2 on shares an XCD; grid-wide arrive/release kept
# speedup vs baseline: 1.0449x; 1.0145x over previous
; __device__ __forceinline__ void own_barrier(unsigned* cnt, unsigned G) {
;     asm volatile("s_waitcnt vmcnt(0) lgkmcnt(0)" ::: "memory");
;     __syncthreads();
;     if (threadIdx.x == 0) {
;         __builtin_amdgcn_fence(__ATOMIC_RELEASE, "agent"); asm volatile("s_waitcnt vmcnt(0)" ::: "memory");
.LBB0_301:
	s_or_b64 exec, exec, s[0:1]
	v_readfirstlane_b32 s100, v160
	s_cmp_lg_u32 s100, 0
	s_cbranch_scc1 .Lxcd_tbl_skip
	v_mbcnt_lo_u32_b32 v246, -1, 0
	v_mbcnt_hi_u32_b32 v246, -1, v246
	v_lshlrev_b32_e32 v247, 2, v246
	v_add_u32_e32 v247, 0x8e08000, v247
	v_and_b32_e32 v248, 7, v246
	v_lshlrev_b32_e32 v248, 2, v248
	v_add_u32_e32 v248, 0x8e08000, v248
	global_load_dword v249, v247, s[90:91] sc1
	global_load_dword v250, v247, s[90:91] offset:256 sc1
	global_load_dword v251, v247, s[90:91] offset:512 sc1
	global_load_dword v252, v247, s[90:91] offset:768 sc1
	global_load_dword v253, v248, s[90:91] sc1

; __global__ void __launch_bounds__(512, 2) hybrid_fwd(Args a) {
;     ...
;         for (int i0 = bx; i0 < N_A + N_B; i0 += G) {
;             int it = i0;
;             if (xmap) { const int k = i0 / G;
;                 if (i0 < N_A) it = xcd * (N_A / 8) + k * perx + jx;
;                 else { const int kb = (i0 - N_A) / G; it = N_A + xcd * (N_B / 8) + kb * perx + jx; } }
;     ...
;                 const int bi = it - N_A, grp = bi >> 9, rem = bi & 511, hs = rem >> 7, rb = rem & 127;
;                 const int dsh = 2 * grp, d = 1 << dsh;
;                 const int nblk = 128 >> dsh, r = rb / nblk, b = rb % nblk;
.LBB0_309:
	v_readlane_b32 s16, v242, 9
	s_add_i32 s16, s23, s16
	s_nop 0
	v_mov_b32_e32 v1, s16
	s_cmp_lg_u32 s101, 1
	s_cbranch_scc1 .Lp2_noremap
	s_cmp_lt_u32 s22, 0x100
	s_cbranch_scc1 .Lp2_noremap
	s_cmp_lt_u32 s22, 0x1000
	s_cbranch_scc0 .Lp2_extra
	s_lshr_b32 s16, s2, 3
	s_lshr_b32 s17, s22, 8
	s_sub_u32 s17, s17, 1
	s_branch .Lp2_map
.Lp2_extra:
	s_sub_u32 s16, s2, 64
	s_lshr_b32 s17, s16, 6
	s_add_u32 s17, s17, 4
	s_and_b32 s16, s16, 63
	s_lshr_b32 s16, s16, 3
.Lp2_map:
	s_lshl_b32 s17, s17, 5
	s_add_u32 s16, s16, s17
	s_lshr_b32 s17, s16, 6
	s_lshl_b32 s17, s17, 9
	s_bfe_u32 s23, s16, 0x20004
	s_lshl_b32 s23, s23, 7
	s_add_u32 s17, s17, s23
	s_and_b32 s16, s16, 15
	s_add_u32 s17, s17, s16
	s_and_b32 s16, s2, 7
	s_lshl_b32 s16, s16, 4
	s_add_u32 s17, s17, s16
	s_add_u32 s16, s17, 0x100
	v_mov_b32_e32 v1, s16

; __device__ __forceinline__ void own_barrier(unsigned* cnt, unsigned G) {
;     asm volatile("s_waitcnt vmcnt(0) lgkmcnt(0)" ::: "memory");
;     __syncthreads();
;     if (threadIdx.x == 0) {
;         __builtin_amdgcn_fence(__ATOMIC_RELEASE, "agent"); asm volatile("s_waitcnt vmcnt(0)" ::: "memory");
;         unsigned target;
;         if ((G & 7u) == 0u) { target = 8u;
;             const unsigned old = __hip_atomic_fetch_add(cnt + 64 * (1 + (blockIdx.x & 7)), 1u, __ATOMIC_RELAXED, __HIP_MEMORY_SCOPE_AGENT);
;             if (old + 1u == (G >> 3)) __hip_atomic_fetch_add(cnt, 1u, __ATOMIC_RELAXED, __HIP_MEMORY_SCOPE_AGENT); }
;         else { target = G; __hip_atomic_fetch_add(cnt, 1u, __ATOMIC_RELAXED, __HIP_MEMORY_SCOPE_AGENT); }
.LBB0_340:
	s_waitcnt vmcnt(0) lgkmcnt(0)
	s_barrier
	s_mov_b64 s[4:5], exec
	v_readlane_b32 s8, v242, 4
	v_readlane_b32 s9, v242, 5
	s_and_b64 s[8:9], s[4:5], s[8:9]
	s_mov_b64 exec, s[8:9]
	s_cbranch_execz .LBB0_366
	s_cmp_lg_u32 s92, 0x100
	s_cbranch_scc1 .Lseam2_orig
	s_mov_b64 exec, -1
	v_xor_b32_e32 v249, v249, v253
	v_xor_b32_e32 v250, v250, v253
	v_xor_b32_e32 v251, v251, v253
	v_xor_b32_e32 v252, v252, v253
	v_or3_b32 v249, v249, v250, v251
	v_or_b32_e32 v249, v249, v252
	v_readlane_b32 s100, v253, 0
	s_lshl_b32 s100, 1, s100
	s_mov_b32 vcc_lo, s100
	v_readlane_b32 s100, v253, 1
	s_lshl_b32 s100, 1, s100
	s_or_b32 vcc_lo, vcc_lo, s100
	v_readlane_b32 s100, v253, 2
	s_lshl_b32 s100, 1, s100
	s_or_b32 vcc_lo, vcc_lo, s100
	v_readlane_b32 s100, v253, 3
	s_lshl_b32 s100, 1, s100
	s_or_b32 vcc_lo, vcc_lo, s100
	v_readlane_b32 s100, v253, 4
	s_lshl_b32 s100, 1, s100
	s_or_b32 vcc_lo, vcc_lo, s100
	v_readlane_b32 s100, v253, 5
	s_lshl_b32 s100, 1, s100
	s_or_b32 vcc_lo, vcc_lo, s100
	v_readlane_b32 s100, v253, 6
	s_lshl_b32 s100, 1, s100
	s_or_b32 vcc_lo, vcc_lo, s100
	v_readlane_b32 s100, v253, 7
	s_lshl_b32 s100, 1, s100
	s_or_b32 vcc_lo, vcc_lo, s100
	s_cmp_eq_u32 vcc_lo, 0xff
	s_cselect_b32 m0, 1, 0
	v_cmp_ne_u32_e32 vcc, 0, v249
	s_cmp_eq_u64 vcc, 0
	s_cselect_b32 s100, 1, 0
	s_and_b32 s100, s100, m0
	s_mov_b64 exec, 1
	v_writelane_b32 v246, s100, 0
	v_readlane_b32 s100, v246, 0
	s_cmp_eq_u32 s100, 1
	s_cbranch_scc1 .Lseam2_nowb
	buffer_wbl2 sc1
	s_waitcnt vmcnt(0)
.Lseam2_nowb:
	v_mov_b32_e32 v1, 0x8e02000
	v_mov_b32_e32 v2, 1
	global_atomic_add v2, v1, v2, s[90:91] sc0
	s_lshl_b32 s100, s2, 12
	s_add_u32 s100, s100, 0x8e10000
	v_mov_b32_e32 v1, s100
	s_waitcnt vmcnt(0)
	v_readfirstlane_b32 s100, v2
	s_cmp_eq_u32 s100, 0xff
	s_cbranch_scc0 .Lseam2_wait
	s_mov_b64 exec, -1
	v_mbcnt_lo_u32_b32 v243, -1, 0
	v_mbcnt_hi_u32_b32 v243, -1, v243
	v_lshlrev_b32_e32 v243, 12, v243
	v_add_u32_e32 v243, 0x8e10000, v243
	v_mov_b32_e32 v244, 2
	global_store_dword v243, v244, s[90:91] sc1
	v_add_u32_e32 v243, 0x40000, v243
	global_store_dword v243, v244, s[90:91] sc1
	v_add_u32_e32 v243, 0x40000, v243
	global_store_dword v243, v244, s[90:91] sc1
	v_add_u32_e32 v243, 0x40000, v243
	global_store_dword v243, v244, s[90:91] sc1
	s_mov_b64 exec, 1
	s_branch .Lseam2_done

; __device__ __forceinline__ void own_barrier(unsigned* cnt, unsigned G) {
;     ...
;         unsigned spins = 0;
;         while (__hip_atomic_load(cnt, __ATOMIC_RELAXED, __HIP_MEMORY_SCOPE_AGENT) < target && ++spins < (1u << 22)) __builtin_amdgcn_s_sleep(1);
;         __builtin_amdgcn_fence(__ATOMIC_ACQUIRE, "agent"); asm volatile("s_waitcnt vmcnt(0)" ::: "memory");
;     }
;     __syncthreads();
.Lseam2_poll:
	global_load_dword v2, v1, s[90:91] sc1
	s_waitcnt vmcnt(0)
	v_cmp_eq_u32_e32 vcc, 2, v2
	s_cbranch_vccnz .Lseam2_done
	s_sleep 1
	s_add_i32 s100, s100, -1
	s_cmp_lg_u32 s100, 0
	s_cbranch_scc1 .Lseam2_poll
.Lseam2_done:
	v_readlane_b32 s100, v246, 0
	s_cmp_eq_u32 s100, 1
	s_cbranch_scc0 .Lseam2_invl2
	buffer_inv sc0
	s_waitcnt vmcnt(0)
	s_branch .Lseam2_join

; __global__ void __launch_bounds__(512, 2) hybrid_fwd(Args a) {
;     ...
;     {
;         const int gw = bx * 8 + wave, NGW = G * 8;
;         const int hs = lane >> 4, dc = (lane & 15) * 8;
;         for (int t0 = gw; t0 < M; t0 += 2 * NGW) {
;             float lw[2][3]; u32x2 ov[2][3], gv[2]; int tt[2];
; #pragma unroll
;             for (int u = 0; u < 2; ++u) { const int t = (t0 + u * NGW < M) ? t0 + u * NGW : t0; tt[u] = t;
;                 const bf16_t* hp = H + (size_t)t * DIN;
; #pragma unroll
;                 for (int g3 = 0; g3 < 3; ++g3) { lw[u][g3] = LSE[((size_t)g3 * M + t) * 4 + hs]; ov[u][g3] = *(const u32x2*)((const unsigned char*)OG + ((size_t)g3 * M + t) * 512 + hs * 128 + dc); }
;                 gv[u] = *(const u32x2*)((const unsigned char*)(hp + OFF_GB) + hs * 128 + dc); }
.Lseam2_join:
.LBB0_366:
	s_or_b64 exec, exec, s[4:5]
	v_readlane_b32 s4, v242, 1
	s_cmpk_gt_i32 s4, 0x3fff
	s_barrier
	v_readlane_b32 s5, v242, 2
	s_cbranch_scc1 .LBB0_371
	v_readlane_b32 s4, v242, 6
	v_lshlrev_b32_e32 v12, 2, v139
	v_mov_b32_e32 v13, 0
	v_readlane_b32 s5, v242, 7
	v_lshlrev_b32_e32 v4, 7, v139
	v_mov_b32_e32 v5, v13
	v_lshl_add_u64 v[2:3], s[4:5], 0, v[12:13]
	v_readlane_b32 s4, v242, 1
	s_mov_b32 s100, s92
	s_cmp_lg_u32 s92, 0x100
	s_cbranch_scc1 .Lp2b_map_off
	v_readfirstlane_b32 s4, v160
	s_lshr_b32 s4, s4, 6
	s_lshr_b32 s100, s2, 3
	s_lshl_b32 s100, s100, 3
	s_add_u32 s4, s4, s100
	s_and_b32 s100, s2, 7
	s_lshl_b32 s100, s100, 11
	s_add_u32 s4, s4, s100
	s_movk_i32 s72, 0x100
	s_movk_i32 s100, 32
.Lp2b_map_off:
	v_lshl_add_u64 v[6:7], s[0:1], 0, v[4:5]
	s_lshl_b32 s0, s100, 4
	s_mov_b32 s22, s4
	s_ashr_i32 s23, s4, 31
	s_mul_hi_i32 s1, s4, 0x600
	s_mulk_i32 s4, 0x600
	v_readlane_b32 s5, v242, 2
	s_add_u32 s4, s88, s4
	s_addc_u32 s5, s89, s1
	s_ashr_i32 s1, s0, 31
	s_lshl_b64 s[8:9], s[22:23], 4
	v_mov_b32_e32 v1, v13
	v_or_b32_e32 v12, s8, v12
	v_mov_b32_e32 v13, s9
	s_lshl_b64 s[8:9], s[0:1], 4
	s_lshl_b64 s[10:11], s[22:23], 9
	s_add_u32 s10, s88, s10
	s_addc_u32 s11, s89, s11
	v_lshl_add_u64 v[14:15], s[10:11], 0, v[4:5]
	s_lshl_b64 s[10:11], s[0:1], 9
	s_mul_hi_i32 s1, s22, 0x5a00
	s_mul_i32 s12, s22, 0x5a00
	v_and_b32_e32 v0, 0x78, v145
	v_lshl_add_u64 v[8:9], s[94:95], 0, v[4:5]
	v_lshl_add_u64 v[10:11], s[4:5], 0, v[4:5]
	s_mov_b64 s[4:5], 0x2000400
	v_or_b32_e32 v16, s12, v4
	v_mov_b32_e32 v17, s1
	s_mov_b64 s[12:13], 0x9003600
	s_mov_b32 s14, s22
	v_lshl_add_u64 v[6:7], v[6:7], 0, v[0:1]
	v_lshl_add_u64 v[8:9], v[8:9], 0, v[0:1]
	v_lshl_add_u64 v[10:11], v[10:11], 0, s[4:5]
	s_mul_i32 s4, s100, 0x6000
	s_mul_hi_i32 s5, s0, 0x600
	v_lshl_add_u64 v[16:17], v[16:17], 0, s[12:13]
	s_mul_i32 s12, s100, 0x5a000
	s_mul_hi_i32 s13, s0, 0x5a00
	v_lshl_add_u64 v[18:19], s[90:91], 0, v[0:1]
	s_movk_i32 s1, 0x3000
	s_mov_b32 s16, 0x4800000
	s_mov_b32 s17, 0x8880000
	s_brev_b32 s18, 32
	s_mov_b32 s19, 0x8840000
	s_mov_b32 s20, 0x3800000
	s_mov_b32 s21, 0x8800000
	v_mov_b32_e32 v28, 0x600
	v_writelane_b32 v242, s14, 1
	s_nop 1
	v_writelane_b32 v242, s15, 2
	s_movk_i32 s100, 0x4000
	s_cmp_lg_u32 s92, 0x100
	s_cbranch_scc1 .Lp2b_end_off
	s_and_b32 s100, s2, 7
	s_add_u32 s100, s100, 1
	s_lshl_b32 s100, s100, 11

; __global__ void __launch_bounds__(512, 2) hybrid_fwd(Args a) {
;     ...
;         for (int t0 = gw; t0 < M; t0 += 2 * NGW) {
.LBB0_368:
	s_add_i32 s22, s22, s0
	v_lshl_add_u64 v[10:11], v[10:11], 0, s[4:5]
	v_lshl_add_u64 v[12:13], v[12:13], 0, s[8:9]
	v_lshl_add_u64 v[14:15], v[14:15], 0, s[10:11]
	s_cmp_lt_i32 s22, s100
	v_lshl_add_u64 v[16:17], v[16:17], 0, s[12:13]
	s_cbranch_scc0 .LBB0_371

; __device__ __forceinline__ void own_barrier(unsigned* cnt, unsigned G) {
;     asm volatile("s_waitcnt vmcnt(0) lgkmcnt(0)" ::: "memory");
;     __syncthreads();
;     if (threadIdx.x == 0) {
;         __builtin_amdgcn_fence(__ATOMIC_RELEASE, "agent"); asm volatile("s_waitcnt vmcnt(0)" ::: "memory");
;         unsigned target;
;         if ((G & 7u) == 0u) { target = 8u;
;             const unsigned old = __hip_atomic_fetch_add(cnt + 64 * (1 + (blockIdx.x & 7)), 1u, __ATOMIC_RELAXED, __HIP_MEMORY_SCOPE_AGENT);
;             if (old + 1u == (G >> 3)) __hip_atomic_fetch_add(cnt, 1u, __ATOMIC_RELAXED, __HIP_MEMORY_SCOPE_AGENT); }
;         else { target = G; __hip_atomic_fetch_add(cnt, 1u, __ATOMIC_RELAXED, __HIP_MEMORY_SCOPE_AGENT); }
.LBB0_371:
	s_lshl_b32 s72, s92, 3
	s_waitcnt vmcnt(0) lgkmcnt(0)
	v_readlane_b32 s62, v242, 4
	v_readlane_b32 s63, v242, 5
	s_barrier
	s_and_saveexec_b64 s[0:1], s[62:63]
	s_cbranch_execz .LBB0_397
	s_cmp_lg_u32 s92, 0x100
	s_cbranch_scc1 .Lseam3_orig
	v_readlane_b32 s100, v246, 0
	s_cmp_eq_u32 s100, 1
	s_cbranch_scc1 .Lseam3_nowb
	buffer_wbl2 sc1
	s_waitcnt vmcnt(0)
.Lseam3_nowb:
	v_mov_b32_e32 v1, 0x8e03000
	v_mov_b32_e32 v2, 1
	global_atomic_add v2, v1, v2, s[90:91] sc0
	s_lshl_b32 s100, s2, 12
	s_add_u32 s100, s100, 0x8e10000
	v_mov_b32_e32 v1, s100
	s_waitcnt vmcnt(0)
	v_readfirstlane_b32 s100, v2
	s_cmp_eq_u32 s100, 0xff
	s_cbranch_scc0 .Lseam3_wait
	s_mov_b64 exec, -1
	v_mbcnt_lo_u32_b32 v243, -1, 0
	v_mbcnt_hi_u32_b32 v243, -1, v243
	v_lshlrev_b32_e32 v243, 12, v243
	v_add_u32_e32 v243, 0x8e10000, v243
	v_mov_b32_e32 v244, 3
	global_store_dword v243, v244, s[90:91] sc1
	v_add_u32_e32 v243, 0x40000, v243
	global_store_dword v243, v244, s[90:91] sc1
	v_add_u32_e32 v243, 0x40000, v243
	global_store_dword v243, v244, s[90:91] sc1
	v_add_u32_e32 v243, 0x40000, v243
	global_store_dword v243, v244, s[90:91] sc1
	s_mov_b64 exec, 1
	s_branch .Lseam3_done

; __device__ __forceinline__ void own_barrier(unsigned* cnt, unsigned G) {
;     ...
;         unsigned spins = 0;
;         while (__hip_atomic_load(cnt, __ATOMIC_RELAXED, __HIP_MEMORY_SCOPE_AGENT) < target && ++spins < (1u << 22)) __builtin_amdgcn_s_sleep(1);
;         __builtin_amdgcn_fence(__ATOMIC_ACQUIRE, "agent"); asm volatile("s_waitcnt vmcnt(0)" ::: "memory");
;     }
;     __syncthreads();
.Lseam3_poll:
	global_load_dword v2, v1, s[90:91] sc1
	s_waitcnt vmcnt(0)
	v_cmp_eq_u32_e32 vcc, 3, v2
	s_cbranch_vccnz .Lseam3_done
	s_sleep 1
	s_add_i32 s100, s100, -1
	s_cmp_lg_u32 s100, 0
	s_cbranch_scc1 .Lseam3_poll
.Lseam3_done:
	v_readlane_b32 s100, v246, 0
	s_cmp_eq_u32 s100, 1
	s_cbranch_scc0 .Lseam3_invl2
	buffer_inv sc0
	s_waitcnt vmcnt(0)
	s_branch .Lseam3_join
